# v_combo7 + sort network writes the key lists straight into the pair registers (no setup moves)
# speedup vs baseline: 1.0159x; 1.0006x over previous
.LBB0_1346:
	s_mov_b32 s78, 0x10001
	s_mov_b32 s79, 0x10001
	v_mov_b32_e32 v70, 0
	v_mov_b32_e32 v71, 0
	v_add_co_u32_e32 v2, vcc, 0xe000, v0
	s_mov_b32 s40, 0
	s_nop 0
	v_addc_co_u32_e32 v3, vcc, 0, v1, vcc
	v_add_co_u32_e32 v4, vcc, 0xc000, v0
	s_mov_b64 s[0:1], vcc
	v_add_co_u32_e32 v6, vcc, 0xa000, v0
	s_nop 1
	v_addc_co_u32_e32 v7, vcc, 0, v1, vcc
	v_add_co_u32_e32 v8, vcc, 0x8000, v0
	s_nop 1
	v_addc_co_u32_e32 v9, vcc, 0, v1, vcc
	v_add_co_u32_e32 v10, vcc, 0x6000, v0
	s_nop 1
	v_addc_co_u32_e32 v11, vcc, 0, v1, vcc
	v_add_co_u32_e32 v14, vcc, 0x4000, v0
	s_nop 1
	v_addc_co_u32_e32 v15, vcc, 0, v1, vcc
	v_add_co_u32_e32 v18, vcc, 0x2000, v0
	s_nop 1
	v_addc_co_u32_e32 v19, vcc, 0, v1, vcc
	global_load_dwordx4 v[18:21], v[18:19], off
	s_nop 0
	global_load_dwordx4 v[22:25], v[0:1], off
	global_load_dwordx4 v[26:29], v[10:11], off
	global_load_dwordx4 v[30:33], v[14:15], off
	global_load_dwordx4 v[34:37], v[6:7], off
	global_load_dwordx4 v[38:41], v[8:9], off
	v_addc_co_u32_e64 v5, vcc, 0, v1, s[0:1]
	global_load_dwordx4 v[42:45], v[4:5], off
	global_load_dwordx4 v[46:49], v[2:3], off
	global_load_dwordx4 v[50:53], v[12:13], off
	global_load_dwordx4 v[54:57], v[12:13], off offset:64
	global_load_dwordx4 v[58:61], v[12:13], off offset:128
	global_load_dwordx4 v[62:65], v[12:13], off offset:192
	s_nop 0
	global_load_dwordx4 v[0:3], v[12:13], off offset:448
	global_load_dwordx4 v[4:7], v[12:13], off offset:384
	global_load_dwordx4 v[8:11], v[12:13], off offset:320
	s_nop 0
	global_load_dwordx4 v[12:15], v[12:13], off offset:256
	s_waitcnt lgkmcnt(0)
	s_barrier
	s_waitcnt vmcnt(14)
	ds_write_b128 v208, v[22:25]
	ds_write_b128 v209, v[18:21]
	s_waitcnt vmcnt(12)
	ds_write_b128 v210, v[30:33]
	ds_write_b128 v211, v[26:29]
	s_waitcnt vmcnt(10)
	ds_write_b128 v212, v[38:41]
	ds_write_b128 v213, v[34:37]
	s_waitcnt vmcnt(9)
	ds_write_b128 v214, v[42:45]
	s_waitcnt vmcnt(8)
	ds_write_b128 v215, v[46:49]
	s_waitcnt lgkmcnt(0)
	s_barrier
	ds_read_b128 v[18:21], v184
	ds_read_b128 v[22:25], v184 offset:64
	s_waitcnt vmcnt(7) lgkmcnt(1)
	v_mfma_f32_16x16x32_bf16 v[18:21], v[50:53], v[18:21], 0
	s_waitcnt vmcnt(6) lgkmcnt(0)
	v_mfma_f32_16x16x32_bf16 v[18:21], v[54:57], v[22:25], v[18:21]
	ds_read_b128 v[22:25], v184 offset:128
	ds_read_b128 v[26:29], v184 offset:192
	s_waitcnt vmcnt(5) lgkmcnt(1)
	v_mfma_f32_16x16x32_bf16 v[18:21], v[58:61], v[22:25], v[18:21]
	s_waitcnt vmcnt(4) lgkmcnt(0)
	v_mfma_f32_16x16x32_bf16 v[18:21], v[62:65], v[26:29], v[18:21]
	ds_read_b128 v[22:25], v184 offset:4352
	ds_read_b128 v[26:29], v184 offset:4416
	s_waitcnt lgkmcnt(1)
	v_mfma_f32_16x16x32_bf16 v[22:25], v[50:53], v[22:25], 0
	s_waitcnt lgkmcnt(0)
	v_mfma_f32_16x16x32_bf16 v[22:25], v[54:57], v[26:29], v[22:25]
	ds_read_b128 v[26:29], v184 offset:4480
	ds_read_b128 v[30:33], v184 offset:4544
	s_waitcnt lgkmcnt(1)
	v_mfma_f32_16x16x32_bf16 v[22:25], v[58:61], v[26:29], v[22:25]
	s_waitcnt lgkmcnt(0)
	v_mfma_f32_16x16x32_bf16 v[22:25], v[62:65], v[30:33], v[22:25]
	ds_read_b128 v[26:29], v184 offset:8704
	ds_read_b128 v[30:33], v184 offset:8768
	s_waitcnt lgkmcnt(1)
	v_mfma_f32_16x16x32_bf16 v[26:29], v[50:53], v[26:29], 0
	s_waitcnt lgkmcnt(0)
	v_mfma_f32_16x16x32_bf16 v[26:29], v[54:57], v[30:33], v[26:29]
	ds_read_b128 v[30:33], v184 offset:8832
	ds_read_b128 v[34:37], v184 offset:8896
	s_waitcnt lgkmcnt(1)
	v_mfma_f32_16x16x32_bf16 v[26:29], v[58:61], v[30:33], v[26:29]
	s_waitcnt lgkmcnt(0)
	v_mfma_f32_16x16x32_bf16 v[26:29], v[62:65], v[34:37], v[26:29]
	ds_read_b128 v[30:33], v184 offset:13056
	ds_read_b128 v[34:37], v184 offset:13120
	s_waitcnt lgkmcnt(1)
	v_mfma_f32_16x16x32_bf16 v[30:33], v[50:53], v[30:33], 0
	s_waitcnt lgkmcnt(0)
	v_mfma_f32_16x16x32_bf16 v[30:33], v[54:57], v[34:37], v[30:33]
	ds_read_b128 v[34:37], v184 offset:13184
	ds_read_b128 v[38:41], v184 offset:13248
	s_waitcnt lgkmcnt(1)
	v_mfma_f32_16x16x32_bf16 v[30:33], v[58:61], v[34:37], v[30:33]
	s_waitcnt lgkmcnt(0)
	v_mfma_f32_16x16x32_bf16 v[30:33], v[62:65], v[38:41], v[30:33]
	ds_read_b128 v[34:37], v184 offset:17408
	ds_read_b128 v[38:41], v184 offset:17472
	s_waitcnt lgkmcnt(1)
	v_mfma_f32_16x16x32_bf16 v[34:37], v[50:53], v[34:37], 0
	s_waitcnt lgkmcnt(0)
	v_mfma_f32_16x16x32_bf16 v[34:37], v[54:57], v[38:41], v[34:37]
	ds_read_b128 v[38:41], v184 offset:17536
	ds_read_b128 v[42:45], v184 offset:17600
	s_waitcnt lgkmcnt(1)
	v_mfma_f32_16x16x32_bf16 v[34:37], v[58:61], v[38:41], v[34:37]
	s_waitcnt lgkmcnt(0)
	v_mfma_f32_16x16x32_bf16 v[34:37], v[62:65], v[42:45], v[34:37]
	ds_read_b128 v[38:41], v184 offset:21760
	ds_read_b128 v[42:45], v184 offset:21824
	s_waitcnt lgkmcnt(1)
	v_mfma_f32_16x16x32_bf16 v[38:41], v[50:53], v[38:41], 0
	s_waitcnt lgkmcnt(0)
	v_mfma_f32_16x16x32_bf16 v[38:41], v[54:57], v[42:45], v[38:41]
	ds_read_b128 v[42:45], v184 offset:21888
	ds_read_b128 v[46:49], v184 offset:21952
	s_waitcnt lgkmcnt(1)
	v_mfma_f32_16x16x32_bf16 v[38:41], v[58:61], v[42:45], v[38:41]
	s_waitcnt lgkmcnt(0)
	v_mfma_f32_16x16x32_bf16 v[38:41], v[62:65], v[46:49], v[38:41]
	ds_read_b128 v[42:45], v184 offset:26112
	ds_read_b128 v[46:49], v184 offset:26176
	s_waitcnt lgkmcnt(1)
	v_mfma_f32_16x16x32_bf16 v[42:45], v[50:53], v[42:45], 0
	s_waitcnt lgkmcnt(0)
	v_mfma_f32_16x16x32_bf16 v[42:45], v[54:57], v[46:49], v[42:45]
	ds_read_b128 v[46:49], v184 offset:26240
	ds_read_b128 v[66:69], v184 offset:26304
	s_waitcnt lgkmcnt(1)
	v_mfma_f32_16x16x32_bf16 v[42:45], v[58:61], v[46:49], v[42:45]
	s_waitcnt lgkmcnt(0)
	v_mfma_f32_16x16x32_bf16 v[42:45], v[62:65], v[66:69], v[42:45]
	ds_read_b128 v[46:49], v184 offset:30464
	ds_read_b128 v[66:69], v184 offset:30528
	s_waitcnt lgkmcnt(1)
	v_mfma_f32_16x16x32_bf16 v[46:49], v[50:53], v[46:49], 0
	s_waitcnt lgkmcnt(0)
	v_mfma_f32_16x16x32_bf16 v[46:49], v[54:57], v[66:69], v[46:49]
	ds_read_b128 v[50:53], v184 offset:30592
	ds_read_b128 v[54:57], v184 offset:30656
	s_waitcnt lgkmcnt(1)
	v_mfma_f32_16x16x32_bf16 v[46:49], v[58:61], v[50:53], v[46:49]
	s_waitcnt lgkmcnt(0)
	v_mfma_f32_16x16x32_bf16 v[46:49], v[62:65], v[54:57], v[46:49]
	s_nop 7
	s_nop 1
	v_ashrrev_i32_e32 v50, 31, v49
	v_bitop3_b32 v49, v49, v50, v217 bitop3:0x1e
	v_and_or_b32 v49, v49, s67, v178
	v_ashrrev_i32_e32 v50, 31, v45
	v_bitop3_b32 v45, v45, v50, v217 bitop3:0x1e
	v_and_or_b32 v50, v45, s67, v177
	v_ashrrev_i32_e32 v45, 31, v41
	v_bitop3_b32 v41, v41, v45, v217 bitop3:0x1e
	v_and_or_b32 v51, v41, s67, v176
	v_ashrrev_i32_e32 v41, 31, v37
	v_bitop3_b32 v37, v37, v41, v217 bitop3:0x1e
	v_and_or_b32 v52, v37, s67, v175
	v_ashrrev_i32_e32 v37, 31, v33
	v_bitop3_b32 v33, v33, v37, v217 bitop3:0x1e
	v_and_or_b32 v53, v33, s67, v170
	v_ashrrev_i32_e32 v33, 31, v29
	v_bitop3_b32 v29, v29, v33, v217 bitop3:0x1e
	v_and_or_b32 v54, v29, s67, v181
	v_ashrrev_i32_e32 v29, 31, v25
	v_bitop3_b32 v25, v25, v29, v217 bitop3:0x1e
	v_and_or_b32 v55, v25, s67, v180
	v_ashrrev_i32_e32 v25, 31, v21
	v_bitop3_b32 v21, v21, v25, v217 bitop3:0x1e
	v_and_or_b32 v21, v21, s67, v179
	v_ashrrev_i32_e32 v25, 31, v48
	v_bitop3_b32 v25, v48, v25, v217 bitop3:0x1e
	v_and_or_b32 v41, v25, s67, v178
	v_ashrrev_i32_e32 v25, 31, v44
	v_bitop3_b32 v25, v44, v25, v217 bitop3:0x1e
	v_and_or_b32 v44, v25, s67, v177
	v_ashrrev_i32_e32 v25, 31, v40
	v_bitop3_b32 v25, v40, v25, v217 bitop3:0x1e
	v_and_or_b32 v40, v25, s67, v176
	v_ashrrev_i32_e32 v25, 31, v36
	v_bitop3_b32 v25, v36, v25, v217 bitop3:0x1e
	v_and_or_b32 v45, v25, s67, v175
	v_ashrrev_i32_e32 v25, 31, v32
	v_bitop3_b32 v25, v32, v25, v217 bitop3:0x1e
	v_and_or_b32 v48, v25, s67, v170
	v_ashrrev_i32_e32 v25, 31, v28
	v_bitop3_b32 v25, v28, v25, v217 bitop3:0x1e
	v_and_or_b32 v56, v25, s67, v181
	v_ashrrev_i32_e32 v25, 31, v24
	v_bitop3_b32 v24, v24, v25, v217 bitop3:0x1e
	v_and_or_b32 v57, v24, s67, v180
	v_ashrrev_i32_e32 v24, 31, v20
	v_bitop3_b32 v20, v20, v24, v217 bitop3:0x1e
	v_and_or_b32 v20, v20, s67, v179
	v_ashrrev_i32_e32 v24, 31, v47
	v_bitop3_b32 v24, v47, v24, v217 bitop3:0x1e
	v_and_or_b32 v32, v24, s67, v178
	v_min_u32_e32 v47, v52, v51
	v_ashrrev_i32_e32 v24, 31, v43
	v_bitop3_b32 v24, v43, v24, v217 bitop3:0x1e
	v_and_or_b32 v33, v24, s67, v177
	v_ashrrev_i32_e32 v24, 31, v39
	v_bitop3_b32 v24, v39, v24, v217 bitop3:0x1e
	v_and_or_b32 v36, v24, s67, v176
	v_ashrrev_i32_e32 v24, 31, v35
	v_bitop3_b32 v24, v35, v24, v217 bitop3:0x1e
	v_and_or_b32 v35, v24, s67, v175
	v_ashrrev_i32_e32 v24, 31, v31
	v_bitop3_b32 v24, v31, v24, v217 bitop3:0x1e
	v_and_or_b32 v31, v24, s67, v170
	v_ashrrev_i32_e32 v24, 31, v27
	v_bitop3_b32 v24, v27, v24, v217 bitop3:0x1e
	v_and_or_b32 v37, v24, s67, v181
	v_ashrrev_i32_e32 v24, 31, v23
	v_bitop3_b32 v23, v23, v24, v217 bitop3:0x1e
	v_and_or_b32 v39, v23, s67, v180
	v_ashrrev_i32_e32 v23, 31, v19
	v_bitop3_b32 v19, v19, v23, v217 bitop3:0x1e
	v_and_or_b32 v19, v19, s67, v179
	v_ashrrev_i32_e32 v23, 31, v46
	v_bitop3_b32 v23, v46, v23, v217 bitop3:0x1e
	v_and_or_b32 v23, v23, s67, v178
	v_ashrrev_i32_e32 v24, 31, v42
	v_bitop3_b32 v24, v42, v24, v217 bitop3:0x1e
	v_and_or_b32 v24, v24, s67, v177
	v_ashrrev_i32_e32 v25, 31, v38
	v_bitop3_b32 v25, v38, v25, v217 bitop3:0x1e
	v_and_or_b32 v25, v25, s67, v176
	v_ashrrev_i32_e32 v27, 31, v34
	v_bitop3_b32 v27, v34, v27, v217 bitop3:0x1e
	v_and_or_b32 v27, v27, s67, v175
	v_ashrrev_i32_e32 v28, 31, v30
	v_bitop3_b32 v28, v30, v28, v217 bitop3:0x1e
	v_and_or_b32 v28, v28, s67, v170
	v_ashrrev_i32_e32 v29, 31, v26
	v_bitop3_b32 v26, v26, v29, v217 bitop3:0x1e
	v_and_or_b32 v26, v26, s67, v181
	v_ashrrev_i32_e32 v29, 31, v22
	v_bitop3_b32 v22, v22, v29, v217 bitop3:0x1e
	v_and_or_b32 v22, v22, s67, v180
	v_ashrrev_i32_e32 v29, 31, v18
	v_bitop3_b32 v18, v18, v29, v217 bitop3:0x1e
	v_and_or_b32 v18, v18, s67, v179
	v_max_u32_e32 v29, v18, v22
	v_min_u32_e32 v18, v18, v22
	v_max_u32_e32 v22, v26, v28
	v_min_u32_e32 v26, v26, v28
	v_max_u32_e32 v28, v27, v25
	v_min_u32_e32 v25, v27, v25
	v_max_u32_e32 v27, v24, v23
	v_min_u32_e32 v23, v24, v23
	v_max_u32_e32 v24, v29, v22
	v_min_u32_e32 v22, v29, v22
	v_max_u32_e32 v29, v18, v26
	v_min_u32_e32 v18, v18, v26
	v_max_u32_e32 v26, v28, v27
	v_min_u32_e32 v27, v28, v27
	v_max_u32_e32 v28, v25, v23
	v_min_u32_e32 v23, v25, v23
	v_max_u32_e32 v25, v29, v22
	v_min_u32_e32 v29, v29, v22
	v_max_u32_e32 v30, v28, v27
	v_min_u32_e32 v27, v28, v27
	v_max_u32_e32 v80, v24, v26
	v_min_u32_e32 v24, v24, v26
	v_max_u32_e32 v26, v25, v30
	v_min_u32_e32 v25, v25, v30
	v_max_u32_e32 v28, v29, v27
	v_min_u32_e32 v29, v29, v27
	v_max_u32_e32 v27, v18, v23
	v_min_u32_e32 v87, v18, v23
	v_max_u32_e32 v18, v28, v24
	v_min_u32_e32 v28, v28, v24
	v_max_u32_e32 v30, v27, v25
	v_min_u32_e32 v34, v27, v25
	v_max_u32_e32 v81, v26, v18
	v_min_u32_e32 v82, v26, v18
	v_max_u32_e32 v83, v30, v28
	v_min_u32_e32 v84, v30, v28
	v_max_u32_e32 v85, v34, v29
	v_min_u32_e32 v86, v34, v29
	v_max_u32_e32 v18, v19, v39
	v_min_u32_e32 v19, v19, v39
	v_max_u32_e32 v30, v37, v31
	v_min_u32_e32 v31, v37, v31
	v_max_u32_e32 v34, v35, v36
	v_min_u32_e32 v35, v35, v36
	v_max_u32_e32 v36, v33, v32
	v_min_u32_e32 v32, v33, v32
	v_max_u32_e32 v33, v18, v30
	v_min_u32_e32 v18, v18, v30
	v_max_u32_e32 v30, v19, v31
	v_min_u32_e32 v19, v19, v31
	v_max_u32_e32 v31, v34, v36
	v_min_u32_e32 v34, v34, v36
	v_max_u32_e32 v36, v35, v32
	v_min_u32_e32 v32, v35, v32
	v_max_u32_e32 v35, v30, v18
	v_min_u32_e32 v18, v30, v18
	v_max_u32_e32 v37, v36, v34
	v_min_u32_e32 v34, v36, v34
	v_max_u32_e32 v72, v33, v31
	v_min_u32_e32 v33, v33, v31
	v_max_u32_e32 v36, v35, v37
	v_min_u32_e32 v35, v35, v37
	v_max_u32_e32 v37, v18, v34
	v_min_u32_e32 v18, v18, v34
	v_max_u32_e32 v34, v19, v32
	v_min_u32_e32 v79, v19, v32
	v_max_u32_e32 v19, v37, v33
	v_min_u32_e32 v37, v37, v33
	v_max_u32_e32 v38, v34, v35
	v_min_u32_e32 v39, v34, v35
	v_max_u32_e32 v73, v36, v19
	v_min_u32_e32 v74, v36, v19
	v_max_u32_e32 v75, v38, v37
	v_min_u32_e32 v76, v38, v37
	v_max_u32_e32 v77, v39, v18
	v_min_u32_e32 v78, v39, v18
	v_max_u32_e32 v18, v20, v57
	v_min_u32_e32 v19, v20, v57
	v_max_u32_e32 v20, v56, v48
	v_min_u32_e32 v38, v56, v48
	v_max_u32_e32 v39, v45, v40
	v_min_u32_e32 v40, v45, v40
	v_max_u32_e32 v42, v44, v41
	v_min_u32_e32 v41, v44, v41
	v_max_u32_e32 v43, v18, v20
	v_min_u32_e32 v18, v18, v20
	v_max_u32_e32 v20, v19, v38
	v_min_u32_e32 v19, v19, v38
	v_max_u32_e32 v44, v39, v42
	v_min_u32_e32 v38, v39, v42
	v_max_u32_e32 v39, v40, v41
	v_min_u32_e32 v40, v40, v41
	v_max_u32_e32 v41, v20, v18
	v_min_u32_e32 v18, v20, v18
	v_max_u32_e32 v20, v39, v38
	v_min_u32_e32 v39, v39, v38
	v_max_u32_e32 v88, v43, v44
	v_min_u32_e32 v42, v43, v44
	v_max_u32_e32 v43, v41, v20
	v_min_u32_e32 v20, v41, v20
	v_max_u32_e32 v41, v18, v39
	v_max_u32_e32 v44, v19, v40
	v_min_u32_e32 v18, v18, v39
	v_min_u32_e32 v95, v19, v40
	v_max_u32_e32 v19, v41, v42
	v_min_u32_e32 v45, v41, v42
	v_max_u32_e32 v46, v44, v20
	v_min_u32_e32 v20, v44, v20
	v_max_u32_e32 v89, v43, v19
	v_min_u32_e32 v90, v43, v19
	v_max_u32_e32 v91, v46, v45
	v_min_u32_e32 v92, v46, v45
	v_max_u32_e32 v93, v20, v18
	v_min_u32_e32 v94, v20, v18
	v_max_u32_e32 v18, v21, v55
	v_min_u32_e32 v19, v21, v55
	v_max_u32_e32 v20, v54, v53
	v_min_u32_e32 v21, v54, v53
	v_max_u32_e32 v46, v52, v51
	v_max_u32_e32 v48, v50, v49
	v_min_u32_e32 v49, v50, v49
	v_max_u32_e32 v50, v18, v20
	v_min_u32_e32 v18, v18, v20
	v_max_u32_e32 v20, v19, v21
	v_min_u32_e32 v19, v19, v21
	v_max_u32_e32 v21, v46, v48
	v_min_u32_e32 v46, v46, v48
	v_max_u32_e32 v48, v47, v49
	v_min_u32_e32 v47, v47, v49
	v_max_u32_e32 v49, v20, v18
	v_min_u32_e32 v18, v20, v18
	v_max_u32_e32 v20, v48, v46
	v_min_u32_e32 v48, v48, v46
	v_max_u32_e32 v96, v50, v21
	v_min_u32_e32 v21, v50, v21
	v_max_u32_e32 v50, v49, v20
	v_min_u32_e32 v20, v49, v20
	v_max_u32_e32 v49, v18, v48
	v_min_u32_e32 v18, v18, v48
	v_max_u32_e32 v48, v19, v47
	v_min_u32_e32 v103, v19, v47
	v_max_u32_e32 v19, v49, v21
	v_min_u32_e32 v21, v49, v21
	v_max_u32_e32 v51, v48, v20
	v_min_u32_e32 v20, v48, v20
	v_max_u32_e32 v97, v50, v19
	v_min_u32_e32 v98, v50, v19
	v_max_u32_e32 v99, v51, v21
	v_min_u32_e32 v100, v51, v21
	v_max_u32_e32 v101, v20, v18
	v_min_u32_e32 v102, v20, v18
	v_mov_b32_e32 v18, 0
	v_mov_b32_e32 v19, 0
	v_mov_b32_e32 v20, 0
	v_mov_b32_e32 v21, 0
.LBB0_1347:
	v_max_u32_dpp v55, v72, v72 row_ror:1 row_mask:0xf bank_mask:0xf bound_ctrl:1
	v_max_u32_dpp v54, v80, v80 row_ror:1 row_mask:0xf bank_mask:0xf bound_ctrl:1
	v_max_u32_dpp v56, v88, v88 row_ror:1 row_mask:0xf bank_mask:0xf bound_ctrl:1
	v_max_u32_dpp v55, v55, v55 row_ror:2 row_mask:0xf bank_mask:0xf bound_ctrl:1
	v_max_u32_dpp v57, v96, v96 row_ror:1 row_mask:0xf bank_mask:0xf bound_ctrl:1
	v_max_u32_dpp v54, v54, v54 row_ror:2 row_mask:0xf bank_mask:0xf bound_ctrl:1
	v_max_u32_dpp v56, v56, v56 row_ror:2 row_mask:0xf bank_mask:0xf bound_ctrl:1
	v_max_u32_dpp v55, v55, v55 row_ror:4 row_mask:0xf bank_mask:0xf bound_ctrl:1
	v_max_u32_dpp v57, v57, v57 row_ror:2 row_mask:0xf bank_mask:0xf bound_ctrl:1
	v_max_u32_dpp v54, v54, v54 row_ror:4 row_mask:0xf bank_mask:0xf bound_ctrl:1
	v_max_u32_dpp v56, v56, v56 row_ror:4 row_mask:0xf bank_mask:0xf bound_ctrl:1
	v_max_u32_dpp v55, v55, v55 row_ror:8 row_mask:0xf bank_mask:0xf bound_ctrl:1
	v_max_u32_dpp v57, v57, v57 row_ror:4 row_mask:0xf bank_mask:0xf bound_ctrl:1
	v_max_u32_dpp v54, v54, v54 row_ror:8 row_mask:0xf bank_mask:0xf bound_ctrl:1
	v_max_u32_dpp v56, v56, v56 row_ror:8 row_mask:0xf bank_mask:0xf bound_ctrl:1
	v_max_u32_dpp v57, v57, v57 row_ror:8 row_mask:0xf bank_mask:0xf bound_ctrl:1
	v_cmp_eq_u32_e64 s[84:85], v72, v55
	v_cmp_eq_u32_e64 s[86:87], v80, v54
	v_cmp_eq_u32_e64 s[88:89], v88, v56
	v_cmp_eq_u32_e64 s[90:91], v96, v57
	s_mov_b64 exec, s[84:85]
	v_pk_mov_b32 v[72:73], v[72:73], v[74:75] op_sel:[1,0] op_sel_hi:[1,0]
	v_pk_mov_b32 v[74:75], v[74:75], v[76:77] op_sel:[1,0] op_sel_hi:[1,0]
	v_pk_mov_b32 v[76:77], v[76:77], v[78:79] op_sel:[1,0] op_sel_hi:[1,0]
	v_pk_mov_b32 v[78:79], v[78:79], v[70:71] op_sel:[1,0] op_sel_hi:[1,0]
	s_mov_b64 exec, s[86:87]
	v_pk_mov_b32 v[80:81], v[80:81], v[82:83] op_sel:[1,0] op_sel_hi:[1,0]
	v_pk_mov_b32 v[82:83], v[82:83], v[84:85] op_sel:[1,0] op_sel_hi:[1,0]
	v_pk_mov_b32 v[84:85], v[84:85], v[86:87] op_sel:[1,0] op_sel_hi:[1,0]
	v_pk_mov_b32 v[86:87], v[86:87], v[70:71] op_sel:[1,0] op_sel_hi:[1,0]
	s_mov_b64 exec, s[88:89]
	v_pk_mov_b32 v[88:89], v[88:89], v[90:91] op_sel:[1,0] op_sel_hi:[1,0]
	v_pk_mov_b32 v[90:91], v[90:91], v[92:93] op_sel:[1,0] op_sel_hi:[1,0]
	v_pk_mov_b32 v[92:93], v[92:93], v[94:95] op_sel:[1,0] op_sel_hi:[1,0]
	v_pk_mov_b32 v[94:95], v[94:95], v[70:71] op_sel:[1,0] op_sel_hi:[1,0]
	s_mov_b64 exec, s[90:91]
	v_pk_mov_b32 v[96:97], v[96:97], v[98:99] op_sel:[1,0] op_sel_hi:[1,0]
	v_pk_mov_b32 v[98:99], v[98:99], v[100:101] op_sel:[1,0] op_sel_hi:[1,0]
	v_pk_mov_b32 v[100:101], v[100:101], v[102:103] op_sel:[1,0] op_sel_hi:[1,0]
	v_pk_mov_b32 v[102:103], v[102:103], v[70:71] op_sel:[1,0] op_sel_hi:[1,0]
	s_lshl_b64 exec, s[78:79], s40
	s_add_i32 s40, s40, 1
	v_pk_mov_b32 v[18:19], v[54:55], v[54:55] op_sel:[0,1] op_sel_hi:[0,1]
	v_pk_mov_b32 v[20:21], v[56:57], v[56:57] op_sel:[0,1] op_sel_hi:[0,1]
	s_mov_b64 exec, -1
	s_cmp_lg_u32 s40, 8
	s_cbranch_scc1 .LBB0_1347
	v_max_u32_dpp v55, v72, v72 row_ror:1 row_mask:0xf bank_mask:0xf bound_ctrl:1
	v_max_u32_dpp v54, v80, v80 row_ror:1 row_mask:0xf bank_mask:0xf bound_ctrl:1
	v_max_u32_dpp v56, v88, v88 row_ror:1 row_mask:0xf bank_mask:0xf bound_ctrl:1
	v_max_u32_dpp v55, v55, v55 row_ror:2 row_mask:0xf bank_mask:0xf bound_ctrl:1
	v_max_u32_dpp v57, v96, v96 row_ror:1 row_mask:0xf bank_mask:0xf bound_ctrl:1
	v_max_u32_dpp v54, v54, v54 row_ror:2 row_mask:0xf bank_mask:0xf bound_ctrl:1
	v_max_u32_dpp v56, v56, v56 row_ror:2 row_mask:0xf bank_mask:0xf bound_ctrl:1
	v_max_u32_dpp v55, v55, v55 row_ror:4 row_mask:0xf bank_mask:0xf bound_ctrl:1
	v_max_u32_dpp v57, v57, v57 row_ror:2 row_mask:0xf bank_mask:0xf bound_ctrl:1
	v_max_u32_dpp v54, v54, v54 row_ror:4 row_mask:0xf bank_mask:0xf bound_ctrl:1
	v_max_u32_dpp v56, v56, v56 row_ror:4 row_mask:0xf bank_mask:0xf bound_ctrl:1
	v_max_u32_dpp v55, v55, v55 row_ror:8 row_mask:0xf bank_mask:0xf bound_ctrl:1
	v_max_u32_dpp v57, v57, v57 row_ror:4 row_mask:0xf bank_mask:0xf bound_ctrl:1
	v_max_u32_dpp v54, v54, v54 row_ror:8 row_mask:0xf bank_mask:0xf bound_ctrl:1
	v_max_u32_dpp v56, v56, v56 row_ror:8 row_mask:0xf bank_mask:0xf bound_ctrl:1
	v_max_u32_dpp v57, v57, v57 row_ror:8 row_mask:0xf bank_mask:0xf bound_ctrl:1
	v_cmp_eq_u32_e64 s[84:85], v72, v55
	v_cmp_eq_u32_e64 s[86:87], v80, v54
	v_cmp_eq_u32_e64 s[88:89], v88, v56
	v_cmp_eq_u32_e64 s[90:91], v96, v57
	s_mov_b64 exec, s[84:85]
	v_pk_mov_b32 v[72:73], v[72:73], v[74:75] op_sel:[1,0] op_sel_hi:[1,0]
	v_pk_mov_b32 v[74:75], v[74:75], v[76:77] op_sel:[1,0] op_sel_hi:[1,0]
	v_pk_mov_b32 v[76:77], v[76:77], v[78:79] op_sel:[1,0] op_sel_hi:[1,0]
	v_pk_mov_b32 v[78:79], v[78:79], v[70:71] op_sel:[1,0] op_sel_hi:[1,0]
	s_mov_b64 exec, s[86:87]
	v_pk_mov_b32 v[80:81], v[80:81], v[82:83] op_sel:[1,0] op_sel_hi:[1,0]
	v_pk_mov_b32 v[82:83], v[82:83], v[84:85] op_sel:[1,0] op_sel_hi:[1,0]
	v_pk_mov_b32 v[84:85], v[84:85], v[86:87] op_sel:[1,0] op_sel_hi:[1,0]
	v_pk_mov_b32 v[86:87], v[86:87], v[70:71] op_sel:[1,0] op_sel_hi:[1,0]
	s_mov_b64 exec, s[88:89]
	v_pk_mov_b32 v[88:89], v[88:89], v[90:91] op_sel:[1,0] op_sel_hi:[1,0]
	v_pk_mov_b32 v[90:91], v[90:91], v[92:93] op_sel:[1,0] op_sel_hi:[1,0]
	v_pk_mov_b32 v[92:93], v[92:93], v[94:95] op_sel:[1,0] op_sel_hi:[1,0]
	v_pk_mov_b32 v[94:95], v[94:95], v[70:71] op_sel:[1,0] op_sel_hi:[1,0]
	s_mov_b64 exec, s[90:91]
	v_pk_mov_b32 v[96:97], v[96:97], v[98:99] op_sel:[1,0] op_sel_hi:[1,0]
	v_pk_mov_b32 v[98:99], v[98:99], v[100:101] op_sel:[1,0] op_sel_hi:[1,0]
	v_pk_mov_b32 v[100:101], v[100:101], v[102:103] op_sel:[1,0] op_sel_hi:[1,0]
	v_pk_mov_b32 v[102:103], v[102:103], v[70:71] op_sel:[1,0] op_sel_hi:[1,0]
	s_lshl_b64 exec, s[78:79], s40
	s_add_i32 s40, s40, 1
	v_pk_mov_b32 v[18:19], v[54:55], v[54:55] op_sel:[0,1] op_sel_hi:[0,1]
	v_pk_mov_b32 v[20:21], v[56:57], v[56:57] op_sel:[0,1] op_sel_hi:[0,1]
	s_mov_b64 exec, -1
	v_max_u32_dpp v55, v72, v72 row_ror:1 row_mask:0xf bank_mask:0xf bound_ctrl:1
	v_max_u32_dpp v54, v80, v80 row_ror:1 row_mask:0xf bank_mask:0xf bound_ctrl:1
	v_max_u32_dpp v56, v88, v88 row_ror:1 row_mask:0xf bank_mask:0xf bound_ctrl:1
	v_max_u32_dpp v55, v55, v55 row_ror:2 row_mask:0xf bank_mask:0xf bound_ctrl:1
	v_max_u32_dpp v57, v96, v96 row_ror:1 row_mask:0xf bank_mask:0xf bound_ctrl:1
	v_max_u32_dpp v54, v54, v54 row_ror:2 row_mask:0xf bank_mask:0xf bound_ctrl:1
	v_max_u32_dpp v56, v56, v56 row_ror:2 row_mask:0xf bank_mask:0xf bound_ctrl:1
	v_max_u32_dpp v55, v55, v55 row_ror:4 row_mask:0xf bank_mask:0xf bound_ctrl:1
	v_max_u32_dpp v57, v57, v57 row_ror:2 row_mask:0xf bank_mask:0xf bound_ctrl:1
	v_max_u32_dpp v54, v54, v54 row_ror:4 row_mask:0xf bank_mask:0xf bound_ctrl:1
	v_max_u32_dpp v56, v56, v56 row_ror:4 row_mask:0xf bank_mask:0xf bound_ctrl:1
	v_max_u32_dpp v55, v55, v55 row_ror:8 row_mask:0xf bank_mask:0xf bound_ctrl:1
	v_max_u32_dpp v57, v57, v57 row_ror:4 row_mask:0xf bank_mask:0xf bound_ctrl:1
	v_max_u32_dpp v54, v54, v54 row_ror:8 row_mask:0xf bank_mask:0xf bound_ctrl:1
	v_max_u32_dpp v56, v56, v56 row_ror:8 row_mask:0xf bank_mask:0xf bound_ctrl:1
	v_max_u32_dpp v57, v57, v57 row_ror:8 row_mask:0xf bank_mask:0xf bound_ctrl:1
	v_cmp_eq_u32_e64 s[84:85], v72, v55
	v_cmp_eq_u32_e64 s[86:87], v80, v54
	v_cmp_eq_u32_e64 s[88:89], v88, v56
	v_cmp_eq_u32_e64 s[90:91], v96, v57
	s_mov_b64 exec, s[84:85]
	v_pk_mov_b32 v[72:73], v[72:73], v[74:75] op_sel:[1,0] op_sel_hi:[1,0]
	v_pk_mov_b32 v[74:75], v[74:75], v[76:77] op_sel:[1,0] op_sel_hi:[1,0]
	v_pk_mov_b32 v[76:77], v[76:77], v[78:79] op_sel:[1,0] op_sel_hi:[1,0]
	s_mov_b64 exec, s[86:87]
	v_pk_mov_b32 v[80:81], v[80:81], v[82:83] op_sel:[1,0] op_sel_hi:[1,0]
	v_pk_mov_b32 v[82:83], v[82:83], v[84:85] op_sel:[1,0] op_sel_hi:[1,0]
	v_pk_mov_b32 v[84:85], v[84:85], v[86:87] op_sel:[1,0] op_sel_hi:[1,0]
	s_mov_b64 exec, s[88:89]
	v_pk_mov_b32 v[88:89], v[88:89], v[90:91] op_sel:[1,0] op_sel_hi:[1,0]
	v_pk_mov_b32 v[90:91], v[90:91], v[92:93] op_sel:[1,0] op_sel_hi:[1,0]
	v_pk_mov_b32 v[92:93], v[92:93], v[94:95] op_sel:[1,0] op_sel_hi:[1,0]
	s_mov_b64 exec, s[90:91]
	v_pk_mov_b32 v[96:97], v[96:97], v[98:99] op_sel:[1,0] op_sel_hi:[1,0]
	v_pk_mov_b32 v[98:99], v[98:99], v[100:101] op_sel:[1,0] op_sel_hi:[1,0]
	v_pk_mov_b32 v[100:101], v[100:101], v[102:103] op_sel:[1,0] op_sel_hi:[1,0]
	s_lshl_b64 exec, s[78:79], s40
	s_add_i32 s40, s40, 1
	v_pk_mov_b32 v[18:19], v[54:55], v[54:55] op_sel:[0,1] op_sel_hi:[0,1]
	v_pk_mov_b32 v[20:21], v[56:57], v[56:57] op_sel:[0,1] op_sel_hi:[0,1]
	s_mov_b64 exec, -1
	v_max_u32_dpp v55, v72, v72 row_ror:1 row_mask:0xf bank_mask:0xf bound_ctrl:1
	v_max_u32_dpp v54, v80, v80 row_ror:1 row_mask:0xf bank_mask:0xf bound_ctrl:1
	v_max_u32_dpp v56, v88, v88 row_ror:1 row_mask:0xf bank_mask:0xf bound_ctrl:1
	v_max_u32_dpp v55, v55, v55 row_ror:2 row_mask:0xf bank_mask:0xf bound_ctrl:1
	v_max_u32_dpp v57, v96, v96 row_ror:1 row_mask:0xf bank_mask:0xf bound_ctrl:1
	v_max_u32_dpp v54, v54, v54 row_ror:2 row_mask:0xf bank_mask:0xf bound_ctrl:1
	v_max_u32_dpp v56, v56, v56 row_ror:2 row_mask:0xf bank_mask:0xf bound_ctrl:1
	v_max_u32_dpp v55, v55, v55 row_ror:4 row_mask:0xf bank_mask:0xf bound_ctrl:1
	v_max_u32_dpp v57, v57, v57 row_ror:2 row_mask:0xf bank_mask:0xf bound_ctrl:1
	v_max_u32_dpp v54, v54, v54 row_ror:4 row_mask:0xf bank_mask:0xf bound_ctrl:1
	v_max_u32_dpp v56, v56, v56 row_ror:4 row_mask:0xf bank_mask:0xf bound_ctrl:1
	v_max_u32_dpp v55, v55, v55 row_ror:8 row_mask:0xf bank_mask:0xf bound_ctrl:1
	v_max_u32_dpp v57, v57, v57 row_ror:4 row_mask:0xf bank_mask:0xf bound_ctrl:1
	v_max_u32_dpp v54, v54, v54 row_ror:8 row_mask:0xf bank_mask:0xf bound_ctrl:1
	v_max_u32_dpp v56, v56, v56 row_ror:8 row_mask:0xf bank_mask:0xf bound_ctrl:1
	v_max_u32_dpp v57, v57, v57 row_ror:8 row_mask:0xf bank_mask:0xf bound_ctrl:1
	v_cmp_eq_u32_e64 s[84:85], v72, v55
	v_cmp_eq_u32_e64 s[86:87], v80, v54
	v_cmp_eq_u32_e64 s[88:89], v88, v56
	v_cmp_eq_u32_e64 s[90:91], v96, v57
	s_mov_b64 exec, s[84:85]
	v_pk_mov_b32 v[72:73], v[72:73], v[74:75] op_sel:[1,0] op_sel_hi:[1,0]
	v_pk_mov_b32 v[74:75], v[74:75], v[76:77] op_sel:[1,0] op_sel_hi:[1,0]
	v_pk_mov_b32 v[76:77], v[76:77], v[78:79] op_sel:[1,0] op_sel_hi:[1,0]
	s_mov_b64 exec, s[86:87]
	v_pk_mov_b32 v[80:81], v[80:81], v[82:83] op_sel:[1,0] op_sel_hi:[1,0]
	v_pk_mov_b32 v[82:83], v[82:83], v[84:85] op_sel:[1,0] op_sel_hi:[1,0]
	v_pk_mov_b32 v[84:85], v[84:85], v[86:87] op_sel:[1,0] op_sel_hi:[1,0]
	s_mov_b64 exec, s[88:89]
	v_pk_mov_b32 v[88:89], v[88:89], v[90:91] op_sel:[1,0] op_sel_hi:[1,0]
	v_pk_mov_b32 v[90:91], v[90:91], v[92:93] op_sel:[1,0] op_sel_hi:[1,0]
	v_pk_mov_b32 v[92:93], v[92:93], v[94:95] op_sel:[1,0] op_sel_hi:[1,0]
	s_mov_b64 exec, s[90:91]
	v_pk_mov_b32 v[96:97], v[96:97], v[98:99] op_sel:[1,0] op_sel_hi:[1,0]
	v_pk_mov_b32 v[98:99], v[98:99], v[100:101] op_sel:[1,0] op_sel_hi:[1,0]
	v_pk_mov_b32 v[100:101], v[100:101], v[102:103] op_sel:[1,0] op_sel_hi:[1,0]
	s_lshl_b64 exec, s[78:79], s40
	s_add_i32 s40, s40, 1
	v_pk_mov_b32 v[18:19], v[54:55], v[54:55] op_sel:[0,1] op_sel_hi:[0,1]
	v_pk_mov_b32 v[20:21], v[56:57], v[56:57] op_sel:[0,1] op_sel_hi:[0,1]
	s_mov_b64 exec, -1
	v_max_u32_dpp v55, v72, v72 row_ror:1 row_mask:0xf bank_mask:0xf bound_ctrl:1
	v_max_u32_dpp v54, v80, v80 row_ror:1 row_mask:0xf bank_mask:0xf bound_ctrl:1
	v_max_u32_dpp v56, v88, v88 row_ror:1 row_mask:0xf bank_mask:0xf bound_ctrl:1
	v_max_u32_dpp v55, v55, v55 row_ror:2 row_mask:0xf bank_mask:0xf bound_ctrl:1
	v_max_u32_dpp v57, v96, v96 row_ror:1 row_mask:0xf bank_mask:0xf bound_ctrl:1
	v_max_u32_dpp v54, v54, v54 row_ror:2 row_mask:0xf bank_mask:0xf bound_ctrl:1
	v_max_u32_dpp v56, v56, v56 row_ror:2 row_mask:0xf bank_mask:0xf bound_ctrl:1
	v_max_u32_dpp v55, v55, v55 row_ror:4 row_mask:0xf bank_mask:0xf bound_ctrl:1
	v_max_u32_dpp v57, v57, v57 row_ror:2 row_mask:0xf bank_mask:0xf bound_ctrl:1
	v_max_u32_dpp v54, v54, v54 row_ror:4 row_mask:0xf bank_mask:0xf bound_ctrl:1
	v_max_u32_dpp v56, v56, v56 row_ror:4 row_mask:0xf bank_mask:0xf bound_ctrl:1
	v_max_u32_dpp v55, v55, v55 row_ror:8 row_mask:0xf bank_mask:0xf bound_ctrl:1
	v_max_u32_dpp v57, v57, v57 row_ror:4 row_mask:0xf bank_mask:0xf bound_ctrl:1
	v_max_u32_dpp v54, v54, v54 row_ror:8 row_mask:0xf bank_mask:0xf bound_ctrl:1
	v_max_u32_dpp v56, v56, v56 row_ror:8 row_mask:0xf bank_mask:0xf bound_ctrl:1
	v_max_u32_dpp v57, v57, v57 row_ror:8 row_mask:0xf bank_mask:0xf bound_ctrl:1
	v_cmp_eq_u32_e64 s[84:85], v72, v55
	v_cmp_eq_u32_e64 s[86:87], v80, v54
	v_cmp_eq_u32_e64 s[88:89], v88, v56
	v_cmp_eq_u32_e64 s[90:91], v96, v57
	s_mov_b64 exec, s[84:85]
	v_pk_mov_b32 v[72:73], v[72:73], v[74:75] op_sel:[1,0] op_sel_hi:[1,0]
	v_pk_mov_b32 v[74:75], v[74:75], v[76:77] op_sel:[1,0] op_sel_hi:[1,0]
	s_mov_b64 exec, s[86:87]
	v_pk_mov_b32 v[80:81], v[80:81], v[82:83] op_sel:[1,0] op_sel_hi:[1,0]
	v_pk_mov_b32 v[82:83], v[82:83], v[84:85] op_sel:[1,0] op_sel_hi:[1,0]
	s_mov_b64 exec, s[88:89]
	v_pk_mov_b32 v[88:89], v[88:89], v[90:91] op_sel:[1,0] op_sel_hi:[1,0]
	v_pk_mov_b32 v[90:91], v[90:91], v[92:93] op_sel:[1,0] op_sel_hi:[1,0]
	s_mov_b64 exec, s[90:91]
	v_pk_mov_b32 v[96:97], v[96:97], v[98:99] op_sel:[1,0] op_sel_hi:[1,0]
	v_pk_mov_b32 v[98:99], v[98:99], v[100:101] op_sel:[1,0] op_sel_hi:[1,0]
	s_lshl_b64 exec, s[78:79], s40
	s_add_i32 s40, s40, 1
	v_pk_mov_b32 v[18:19], v[54:55], v[54:55] op_sel:[0,1] op_sel_hi:[0,1]
	v_pk_mov_b32 v[20:21], v[56:57], v[56:57] op_sel:[0,1] op_sel_hi:[0,1]
	s_mov_b64 exec, -1
	v_max_u32_dpp v55, v72, v72 row_ror:1 row_mask:0xf bank_mask:0xf bound_ctrl:1
	v_max_u32_dpp v54, v80, v80 row_ror:1 row_mask:0xf bank_mask:0xf bound_ctrl:1
	v_max_u32_dpp v56, v88, v88 row_ror:1 row_mask:0xf bank_mask:0xf bound_ctrl:1
	v_max_u32_dpp v55, v55, v55 row_ror:2 row_mask:0xf bank_mask:0xf bound_ctrl:1
	v_max_u32_dpp v57, v96, v96 row_ror:1 row_mask:0xf bank_mask:0xf bound_ctrl:1
	v_max_u32_dpp v54, v54, v54 row_ror:2 row_mask:0xf bank_mask:0xf bound_ctrl:1
	v_max_u32_dpp v56, v56, v56 row_ror:2 row_mask:0xf bank_mask:0xf bound_ctrl:1
	v_max_u32_dpp v55, v55, v55 row_ror:4 row_mask:0xf bank_mask:0xf bound_ctrl:1
	v_max_u32_dpp v57, v57, v57 row_ror:2 row_mask:0xf bank_mask:0xf bound_ctrl:1
	v_max_u32_dpp v54, v54, v54 row_ror:4 row_mask:0xf bank_mask:0xf bound_ctrl:1
	v_max_u32_dpp v56, v56, v56 row_ror:4 row_mask:0xf bank_mask:0xf bound_ctrl:1
	v_max_u32_dpp v55, v55, v55 row_ror:8 row_mask:0xf bank_mask:0xf bound_ctrl:1
	v_max_u32_dpp v57, v57, v57 row_ror:4 row_mask:0xf bank_mask:0xf bound_ctrl:1
	v_max_u32_dpp v54, v54, v54 row_ror:8 row_mask:0xf bank_mask:0xf bound_ctrl:1
	v_max_u32_dpp v56, v56, v56 row_ror:8 row_mask:0xf bank_mask:0xf bound_ctrl:1
	v_max_u32_dpp v57, v57, v57 row_ror:8 row_mask:0xf bank_mask:0xf bound_ctrl:1
	v_cmp_eq_u32_e64 s[84:85], v72, v55
	v_cmp_eq_u32_e64 s[86:87], v80, v54
	v_cmp_eq_u32_e64 s[88:89], v88, v56
	v_cmp_eq_u32_e64 s[90:91], v96, v57
	s_mov_b64 exec, s[84:85]
	v_pk_mov_b32 v[72:73], v[72:73], v[74:75] op_sel:[1,0] op_sel_hi:[1,0]
	v_pk_mov_b32 v[74:75], v[74:75], v[76:77] op_sel:[1,0] op_sel_hi:[1,0]
	s_mov_b64 exec, s[86:87]
	v_pk_mov_b32 v[80:81], v[80:81], v[82:83] op_sel:[1,0] op_sel_hi:[1,0]
	v_pk_mov_b32 v[82:83], v[82:83], v[84:85] op_sel:[1,0] op_sel_hi:[1,0]
	s_mov_b64 exec, s[88:89]
	v_pk_mov_b32 v[88:89], v[88:89], v[90:91] op_sel:[1,0] op_sel_hi:[1,0]
	v_pk_mov_b32 v[90:91], v[90:91], v[92:93] op_sel:[1,0] op_sel_hi:[1,0]
	s_mov_b64 exec, s[90:91]
	v_pk_mov_b32 v[96:97], v[96:97], v[98:99] op_sel:[1,0] op_sel_hi:[1,0]
	v_pk_mov_b32 v[98:99], v[98:99], v[100:101] op_sel:[1,0] op_sel_hi:[1,0]
	s_lshl_b64 exec, s[78:79], s40
	s_add_i32 s40, s40, 1
	v_pk_mov_b32 v[18:19], v[54:55], v[54:55] op_sel:[0,1] op_sel_hi:[0,1]
	v_pk_mov_b32 v[20:21], v[56:57], v[56:57] op_sel:[0,1] op_sel_hi:[0,1]
	s_mov_b64 exec, -1
	v_max_u32_dpp v55, v72, v72 row_ror:1 row_mask:0xf bank_mask:0xf bound_ctrl:1
	v_max_u32_dpp v54, v80, v80 row_ror:1 row_mask:0xf bank_mask:0xf bound_ctrl:1
	v_max_u32_dpp v56, v88, v88 row_ror:1 row_mask:0xf bank_mask:0xf bound_ctrl:1
	v_max_u32_dpp v55, v55, v55 row_ror:2 row_mask:0xf bank_mask:0xf bound_ctrl:1
	v_max_u32_dpp v57, v96, v96 row_ror:1 row_mask:0xf bank_mask:0xf bound_ctrl:1
	v_max_u32_dpp v54, v54, v54 row_ror:2 row_mask:0xf bank_mask:0xf bound_ctrl:1
	v_max_u32_dpp v56, v56, v56 row_ror:2 row_mask:0xf bank_mask:0xf bound_ctrl:1
	v_max_u32_dpp v55, v55, v55 row_ror:4 row_mask:0xf bank_mask:0xf bound_ctrl:1
	v_max_u32_dpp v57, v57, v57 row_ror:2 row_mask:0xf bank_mask:0xf bound_ctrl:1
	v_max_u32_dpp v54, v54, v54 row_ror:4 row_mask:0xf bank_mask:0xf bound_ctrl:1
	v_max_u32_dpp v56, v56, v56 row_ror:4 row_mask:0xf bank_mask:0xf bound_ctrl:1
	v_max_u32_dpp v55, v55, v55 row_ror:8 row_mask:0xf bank_mask:0xf bound_ctrl:1
	v_max_u32_dpp v57, v57, v57 row_ror:4 row_mask:0xf bank_mask:0xf bound_ctrl:1
	v_max_u32_dpp v54, v54, v54 row_ror:8 row_mask:0xf bank_mask:0xf bound_ctrl:1
	v_max_u32_dpp v56, v56, v56 row_ror:8 row_mask:0xf bank_mask:0xf bound_ctrl:1
	v_max_u32_dpp v57, v57, v57 row_ror:8 row_mask:0xf bank_mask:0xf bound_ctrl:1
	v_cmp_eq_u32_e64 s[84:85], v72, v55
	v_cmp_eq_u32_e64 s[86:87], v80, v54
	v_cmp_eq_u32_e64 s[88:89], v88, v56
	v_cmp_eq_u32_e64 s[90:91], v96, v57
	s_mov_b64 exec, s[84:85]
	v_pk_mov_b32 v[72:73], v[72:73], v[74:75] op_sel:[1,0] op_sel_hi:[1,0]
	s_mov_b64 exec, s[86:87]
	v_pk_mov_b32 v[80:81], v[80:81], v[82:83] op_sel:[1,0] op_sel_hi:[1,0]
	s_mov_b64 exec, s[88:89]
	v_pk_mov_b32 v[88:89], v[88:89], v[90:91] op_sel:[1,0] op_sel_hi:[1,0]
	s_mov_b64 exec, s[90:91]
	v_pk_mov_b32 v[96:97], v[96:97], v[98:99] op_sel:[1,0] op_sel_hi:[1,0]
	s_lshl_b64 exec, s[78:79], s40
	s_add_i32 s40, s40, 1
	v_pk_mov_b32 v[18:19], v[54:55], v[54:55] op_sel:[0,1] op_sel_hi:[0,1]
	v_pk_mov_b32 v[20:21], v[56:57], v[56:57] op_sel:[0,1] op_sel_hi:[0,1]
	s_mov_b64 exec, -1
	v_max_u32_dpp v55, v72, v72 row_ror:1 row_mask:0xf bank_mask:0xf bound_ctrl:1
	v_max_u32_dpp v54, v80, v80 row_ror:1 row_mask:0xf bank_mask:0xf bound_ctrl:1
	v_max_u32_dpp v56, v88, v88 row_ror:1 row_mask:0xf bank_mask:0xf bound_ctrl:1
	v_max_u32_dpp v55, v55, v55 row_ror:2 row_mask:0xf bank_mask:0xf bound_ctrl:1
	v_max_u32_dpp v57, v96, v96 row_ror:1 row_mask:0xf bank_mask:0xf bound_ctrl:1
	v_max_u32_dpp v54, v54, v54 row_ror:2 row_mask:0xf bank_mask:0xf bound_ctrl:1
	v_max_u32_dpp v56, v56, v56 row_ror:2 row_mask:0xf bank_mask:0xf bound_ctrl:1
	v_max_u32_dpp v55, v55, v55 row_ror:4 row_mask:0xf bank_mask:0xf bound_ctrl:1
	v_max_u32_dpp v57, v57, v57 row_ror:2 row_mask:0xf bank_mask:0xf bound_ctrl:1
	v_max_u32_dpp v54, v54, v54 row_ror:4 row_mask:0xf bank_mask:0xf bound_ctrl:1
	v_max_u32_dpp v56, v56, v56 row_ror:4 row_mask:0xf bank_mask:0xf bound_ctrl:1
	v_max_u32_dpp v55, v55, v55 row_ror:8 row_mask:0xf bank_mask:0xf bound_ctrl:1
	v_max_u32_dpp v57, v57, v57 row_ror:4 row_mask:0xf bank_mask:0xf bound_ctrl:1
	v_max_u32_dpp v54, v54, v54 row_ror:8 row_mask:0xf bank_mask:0xf bound_ctrl:1
	v_max_u32_dpp v56, v56, v56 row_ror:8 row_mask:0xf bank_mask:0xf bound_ctrl:1
	v_max_u32_dpp v57, v57, v57 row_ror:8 row_mask:0xf bank_mask:0xf bound_ctrl:1
	v_cmp_eq_u32_e64 s[84:85], v72, v55
	v_cmp_eq_u32_e64 s[86:87], v80, v54
	v_cmp_eq_u32_e64 s[88:89], v88, v56
	v_cmp_eq_u32_e64 s[90:91], v96, v57
	s_mov_b64 exec, s[84:85]
	v_pk_mov_b32 v[72:73], v[72:73], v[74:75] op_sel:[1,0] op_sel_hi:[1,0]
	s_mov_b64 exec, s[86:87]
	v_pk_mov_b32 v[80:81], v[80:81], v[82:83] op_sel:[1,0] op_sel_hi:[1,0]
	s_mov_b64 exec, s[88:89]
	v_pk_mov_b32 v[88:89], v[88:89], v[90:91] op_sel:[1,0] op_sel_hi:[1,0]
	s_mov_b64 exec, s[90:91]
	v_pk_mov_b32 v[96:97], v[96:97], v[98:99] op_sel:[1,0] op_sel_hi:[1,0]
	s_lshl_b64 exec, s[78:79], s40
	s_add_i32 s40, s40, 1
	v_pk_mov_b32 v[18:19], v[54:55], v[54:55] op_sel:[0,1] op_sel_hi:[0,1]
	v_pk_mov_b32 v[20:21], v[56:57], v[56:57] op_sel:[0,1] op_sel_hi:[0,1]
	s_mov_b64 exec, -1
	v_max_u32_dpp v55, v72, v72 row_ror:1 row_mask:0xf bank_mask:0xf bound_ctrl:1
	v_max_u32_dpp v54, v80, v80 row_ror:1 row_mask:0xf bank_mask:0xf bound_ctrl:1
	v_max_u32_dpp v56, v88, v88 row_ror:1 row_mask:0xf bank_mask:0xf bound_ctrl:1
	v_max_u32_dpp v55, v55, v55 row_ror:2 row_mask:0xf bank_mask:0xf bound_ctrl:1
	v_max_u32_dpp v57, v96, v96 row_ror:1 row_mask:0xf bank_mask:0xf bound_ctrl:1
	v_max_u32_dpp v54, v54, v54 row_ror:2 row_mask:0xf bank_mask:0xf bound_ctrl:1
	v_max_u32_dpp v56, v56, v56 row_ror:2 row_mask:0xf bank_mask:0xf bound_ctrl:1
	v_max_u32_dpp v55, v55, v55 row_ror:4 row_mask:0xf bank_mask:0xf bound_ctrl:1
	v_max_u32_dpp v57, v57, v57 row_ror:2 row_mask:0xf bank_mask:0xf bound_ctrl:1
	v_max_u32_dpp v54, v54, v54 row_ror:4 row_mask:0xf bank_mask:0xf bound_ctrl:1
	v_max_u32_dpp v56, v56, v56 row_ror:4 row_mask:0xf bank_mask:0xf bound_ctrl:1
	v_max_u32_dpp v55, v55, v55 row_ror:8 row_mask:0xf bank_mask:0xf bound_ctrl:1
	v_max_u32_dpp v57, v57, v57 row_ror:4 row_mask:0xf bank_mask:0xf bound_ctrl:1
	v_max_u32_dpp v54, v54, v54 row_ror:8 row_mask:0xf bank_mask:0xf bound_ctrl:1
	v_max_u32_dpp v56, v56, v56 row_ror:8 row_mask:0xf bank_mask:0xf bound_ctrl:1
	v_max_u32_dpp v57, v57, v57 row_ror:8 row_mask:0xf bank_mask:0xf bound_ctrl:1
	s_lshl_b64 exec, s[78:79], s40
	v_pk_mov_b32 v[18:19], v[54:55], v[54:55] op_sel:[0,1] op_sel_hi:[0,1]
	v_pk_mov_b32 v[20:21], v[56:57], v[56:57] op_sel:[0,1] op_sel_hi:[0,1]
	s_mov_b64 exec, -1
	ds_read_b128 v[22:25], v184 offset:34816
	ds_read_b128 v[26:29], v184 offset:34880
	s_waitcnt vmcnt(0) lgkmcnt(1)
	v_mfma_f32_16x16x32_bf16 v[22:25], v[12:15], v[22:25], 0
	s_waitcnt lgkmcnt(0)
	v_mfma_f32_16x16x32_bf16 v[22:25], v[8:11], v[26:29], v[22:25]
	ds_read_b128 v[26:29], v184 offset:34944
	s_waitcnt lgkmcnt(0)
	v_mfma_f32_16x16x32_bf16 v[22:25], v[4:7], v[26:29], v[22:25]
	ds_read_b128 v[26:29], v184 offset:35008
	s_waitcnt lgkmcnt(0)
	v_mfma_f32_16x16x32_bf16 v[22:25], v[0:3], v[26:29], v[22:25]
	ds_read_b128 v[26:29], v184 offset:39168
	ds_read_b128 v[30:33], v184 offset:39232
	s_waitcnt lgkmcnt(1)
	v_mfma_f32_16x16x32_bf16 v[26:29], v[12:15], v[26:29], 0
	s_waitcnt lgkmcnt(0)
	v_mfma_f32_16x16x32_bf16 v[26:29], v[8:11], v[30:33], v[26:29]
	ds_read_b128 v[30:33], v184 offset:39296
	ds_read_b128 v[34:37], v184 offset:39360
	s_waitcnt lgkmcnt(1)
	v_mfma_f32_16x16x32_bf16 v[26:29], v[4:7], v[30:33], v[26:29]
	s_waitcnt lgkmcnt(0)
	v_mfma_f32_16x16x32_bf16 v[26:29], v[0:3], v[34:37], v[26:29]
	ds_read_b128 v[30:33], v184 offset:43520
	ds_read_b128 v[34:37], v184 offset:43584
	s_waitcnt lgkmcnt(1)
	v_mfma_f32_16x16x32_bf16 v[30:33], v[12:15], v[30:33], 0
	s_waitcnt lgkmcnt(0)
	v_mfma_f32_16x16x32_bf16 v[30:33], v[8:11], v[34:37], v[30:33]
	ds_read_b128 v[34:37], v184 offset:43648
	ds_read_b128 v[38:41], v184 offset:43712
	s_waitcnt lgkmcnt(1)
	v_mfma_f32_16x16x32_bf16 v[30:33], v[4:7], v[34:37], v[30:33]
	s_waitcnt lgkmcnt(0)
	v_mfma_f32_16x16x32_bf16 v[30:33], v[0:3], v[38:41], v[30:33]
	ds_read_b128 v[34:37], v184 offset:47872
	ds_read_b128 v[38:41], v184 offset:47936
	s_waitcnt lgkmcnt(1)
	v_mfma_f32_16x16x32_bf16 v[34:37], v[12:15], v[34:37], 0
	s_waitcnt lgkmcnt(0)
	v_mfma_f32_16x16x32_bf16 v[34:37], v[8:11], v[38:41], v[34:37]
	ds_read_b128 v[38:41], v184 offset:48000
	ds_read_b128 v[42:45], v184 offset:48064
	s_waitcnt lgkmcnt(1)
	v_mfma_f32_16x16x32_bf16 v[34:37], v[4:7], v[38:41], v[34:37]
	s_waitcnt lgkmcnt(0)
	v_mfma_f32_16x16x32_bf16 v[34:37], v[0:3], v[42:45], v[34:37]
	ds_read_b128 v[38:41], v184 offset:52224
	ds_read_b128 v[42:45], v184 offset:52288
	s_waitcnt lgkmcnt(1)
	v_mfma_f32_16x16x32_bf16 v[38:41], v[12:15], v[38:41], 0
	s_waitcnt lgkmcnt(0)
	v_mfma_f32_16x16x32_bf16 v[38:41], v[8:11], v[42:45], v[38:41]
	ds_read_b128 v[42:45], v184 offset:52352
	ds_read_b128 v[46:49], v184 offset:52416
	s_waitcnt lgkmcnt(1)
	v_mfma_f32_16x16x32_bf16 v[38:41], v[4:7], v[42:45], v[38:41]
	s_waitcnt lgkmcnt(0)
	v_mfma_f32_16x16x32_bf16 v[38:41], v[0:3], v[46:49], v[38:41]
	ds_read_b128 v[42:45], v184 offset:56576
	ds_read_b128 v[46:49], v184 offset:56640
	s_waitcnt lgkmcnt(1)
	v_mfma_f32_16x16x32_bf16 v[42:45], v[12:15], v[42:45], 0
	s_waitcnt lgkmcnt(0)
	v_mfma_f32_16x16x32_bf16 v[42:45], v[8:11], v[46:49], v[42:45]
	ds_read_b128 v[46:49], v184 offset:56704
	ds_read_b128 v[50:53], v184 offset:56768
	s_waitcnt lgkmcnt(1)
	v_mfma_f32_16x16x32_bf16 v[42:45], v[4:7], v[46:49], v[42:45]
	s_waitcnt lgkmcnt(0)
	v_mfma_f32_16x16x32_bf16 v[42:45], v[0:3], v[50:53], v[42:45]
	ds_read_b128 v[46:49], v184 offset:60928
	ds_read_b128 v[50:53], v184 offset:60992
	s_waitcnt lgkmcnt(1)
	v_mfma_f32_16x16x32_bf16 v[46:49], v[12:15], v[46:49], 0
	s_waitcnt lgkmcnt(0)
	v_mfma_f32_16x16x32_bf16 v[46:49], v[8:11], v[50:53], v[46:49]
	ds_read_b128 v[50:53], v184 offset:61056
	ds_read_b128 v[54:57], v184 offset:61120
	s_waitcnt lgkmcnt(1)
	v_mfma_f32_16x16x32_bf16 v[46:49], v[4:7], v[50:53], v[46:49]
	s_waitcnt lgkmcnt(0)
	v_mfma_f32_16x16x32_bf16 v[46:49], v[0:3], v[54:57], v[46:49]
	ds_read_b128 v[50:53], v184 offset:65280
	ds_read_b128 v[54:57], v184 offset:65344
	s_waitcnt lgkmcnt(1)
	v_mfma_f32_16x16x32_bf16 v[12:15], v[12:15], v[50:53], 0
	s_waitcnt lgkmcnt(0)
	v_mfma_f32_16x16x32_bf16 v[8:11], v[8:11], v[54:57], v[12:15]
	s_nop 5
	ds_read_b128 v[12:15], v184 offset:65408
	ds_read_b128 v[50:53], v184 offset:65472
	s_waitcnt lgkmcnt(1)
	v_mfma_f32_16x16x32_bf16 v[4:7], v[4:7], v[12:15], v[8:11]
	s_waitcnt lgkmcnt(0)
	v_mfma_f32_16x16x32_bf16 v[0:3], v[0:3], v[50:53], v[4:7]
	s_nop 7
	s_mov_b32 s40, 0
	v_ashrrev_i32_e32 v4, 31, v3
	v_bitop3_b32 v3, v3, v4, v217 bitop3:0x1e
	v_and_or_b32 v3, v3, s67, v178
	v_ashrrev_i32_e32 v4, 31, v49
	v_bitop3_b32 v4, v49, v4, v217 bitop3:0x1e
	v_and_or_b32 v49, v4, s67, v177
	v_ashrrev_i32_e32 v4, 31, v45
	v_bitop3_b32 v4, v45, v4, v217 bitop3:0x1e
	v_and_or_b32 v45, v4, s67, v176
	v_ashrrev_i32_e32 v4, 31, v41
	v_bitop3_b32 v4, v41, v4, v217 bitop3:0x1e
	v_and_or_b32 v41, v4, s67, v175
	v_ashrrev_i32_e32 v4, 31, v37
	v_bitop3_b32 v4, v37, v4, v217 bitop3:0x1e
	v_and_or_b32 v37, v4, s67, v170
	v_ashrrev_i32_e32 v4, 31, v33
	v_bitop3_b32 v4, v33, v4, v217 bitop3:0x1e
	v_and_or_b32 v50, v4, s67, v181
	v_ashrrev_i32_e32 v4, 31, v29
	v_bitop3_b32 v4, v29, v4, v217 bitop3:0x1e
	v_and_or_b32 v51, v4, s67, v180
	v_ashrrev_i32_e32 v4, 31, v25
	v_bitop3_b32 v4, v25, v4, v217 bitop3:0x1e
	v_and_or_b32 v52, v4, s67, v179
	v_ashrrev_i32_e32 v4, 31, v2
	v_bitop3_b32 v2, v2, v4, v217 bitop3:0x1e
	v_and_or_b32 v2, v2, s67, v178
	v_ashrrev_i32_e32 v4, 31, v48
	v_bitop3_b32 v4, v48, v4, v217 bitop3:0x1e
	v_and_or_b32 v29, v4, s67, v177
	v_ashrrev_i32_e32 v4, 31, v44
	v_bitop3_b32 v4, v44, v4, v217 bitop3:0x1e
	v_and_or_b32 v33, v4, s67, v176
	v_ashrrev_i32_e32 v4, 31, v40
	v_bitop3_b32 v4, v40, v4, v217 bitop3:0x1e
	v_and_or_b32 v40, v4, s67, v175
	v_ashrrev_i32_e32 v4, 31, v36
	v_bitop3_b32 v4, v36, v4, v217 bitop3:0x1e
	v_and_or_b32 v36, v4, s67, v170
	v_ashrrev_i32_e32 v4, 31, v32
	v_bitop3_b32 v4, v32, v4, v217 bitop3:0x1e
	v_and_or_b32 v32, v4, s67, v181
	v_ashrrev_i32_e32 v4, 31, v28
	v_bitop3_b32 v4, v28, v4, v217 bitop3:0x1e
	v_and_or_b32 v28, v4, s67, v180
	v_ashrrev_i32_e32 v4, 31, v24
	v_bitop3_b32 v4, v24, v4, v217 bitop3:0x1e
	v_and_or_b32 v44, v4, s67, v179
	v_ashrrev_i32_e32 v4, 31, v1
	v_bitop3_b32 v1, v1, v4, v217 bitop3:0x1e
	v_and_or_b32 v1, v1, s67, v178
	v_ashrrev_i32_e32 v4, 31, v47
	v_bitop3_b32 v4, v47, v4, v217 bitop3:0x1e
	v_and_or_b32 v12, v4, s67, v177
	v_ashrrev_i32_e32 v4, 31, v43
	v_bitop3_b32 v4, v43, v4, v217 bitop3:0x1e
	v_and_or_b32 v13, v4, s67, v176
	v_ashrrev_i32_e32 v4, 31, v39
	v_bitop3_b32 v4, v39, v4, v217 bitop3:0x1e
	v_and_or_b32 v14, v4, s67, v175
	v_ashrrev_i32_e32 v4, 31, v35
	v_bitop3_b32 v4, v35, v4, v217 bitop3:0x1e
	v_and_or_b32 v15, v4, s67, v170
	v_max_u32_e32 v35, v41, v45
	v_ashrrev_i32_e32 v4, 31, v31
	v_bitop3_b32 v4, v31, v4, v217 bitop3:0x1e
	v_and_or_b32 v24, v4, s67, v181
	v_max_u32_e32 v31, v29, v2
	v_ashrrev_i32_e32 v4, 31, v27
	v_bitop3_b32 v4, v27, v4, v217 bitop3:0x1e
	v_and_or_b32 v25, v4, s67, v180
	v_min_u32_e32 v2, v29, v2
	v_ashrrev_i32_e32 v4, 31, v23
	v_bitop3_b32 v4, v23, v4, v217 bitop3:0x1e
	v_and_or_b32 v23, v4, s67, v179
	v_ashrrev_i32_e32 v4, 31, v0
	v_bitop3_b32 v0, v0, v4, v217 bitop3:0x1e
	v_and_or_b32 v0, v0, s67, v178
	v_ashrrev_i32_e32 v4, 31, v46
	v_bitop3_b32 v4, v46, v4, v217 bitop3:0x1e
	v_and_or_b32 v4, v4, s67, v177
	v_ashrrev_i32_e32 v5, 31, v42
	v_bitop3_b32 v5, v42, v5, v217 bitop3:0x1e
	v_and_or_b32 v5, v5, s67, v176
	v_ashrrev_i32_e32 v6, 31, v38
	v_bitop3_b32 v6, v38, v6, v217 bitop3:0x1e
	v_and_or_b32 v6, v6, s67, v175
	v_ashrrev_i32_e32 v7, 31, v34
	v_bitop3_b32 v7, v34, v7, v217 bitop3:0x1e
	v_and_or_b32 v7, v7, s67, v170
	v_ashrrev_i32_e32 v8, 31, v30
	v_bitop3_b32 v8, v30, v8, v217 bitop3:0x1e
	v_and_or_b32 v8, v8, s67, v181
	v_ashrrev_i32_e32 v9, 31, v26
	v_bitop3_b32 v9, v26, v9, v217 bitop3:0x1e
	v_and_or_b32 v9, v9, s67, v180
	v_ashrrev_i32_e32 v10, 31, v22
	v_bitop3_b32 v10, v22, v10, v217 bitop3:0x1e
	v_and_or_b32 v10, v10, s67, v179
	v_max_u32_e32 v11, v10, v9
	v_min_u32_e32 v9, v10, v9
	v_max_u32_e32 v10, v8, v7
	v_min_u32_e32 v7, v8, v7
	v_max_u32_e32 v8, v6, v5
	v_min_u32_e32 v5, v6, v5
	v_max_u32_e32 v6, v4, v0
	v_min_u32_e32 v0, v4, v0
	v_max_u32_e32 v22, v11, v10
	v_min_u32_e32 v4, v11, v10
	v_max_u32_e32 v10, v9, v7
	v_min_u32_e32 v7, v9, v7
	v_max_u32_e32 v9, v8, v6
	v_min_u32_e32 v6, v8, v6
	v_max_u32_e32 v8, v5, v0
	v_min_u32_e32 v0, v5, v0
	v_max_u32_e32 v5, v10, v4
	v_min_u32_e32 v10, v10, v4
	v_max_u32_e32 v11, v8, v6
	v_min_u32_e32 v6, v8, v6
	v_max_u32_e32 v80, v22, v9
	v_min_u32_e32 v8, v22, v9
	v_max_u32_e32 v9, v5, v11
	v_min_u32_e32 v11, v5, v11
	v_max_u32_e32 v22, v10, v6
	v_min_u32_e32 v26, v10, v6
	v_max_u32_e32 v6, v7, v0
	v_min_u32_e32 v87, v7, v0
	v_max_u32_e32 v0, v22, v8
	v_min_u32_e32 v10, v22, v8
	v_max_u32_e32 v22, v6, v11
	v_min_u32_e32 v11, v6, v11
	v_max_u32_e32 v81, v9, v0
	v_min_u32_e32 v82, v9, v0
	v_max_u32_e32 v83, v22, v10
	v_min_u32_e32 v84, v22, v10
	v_max_u32_e32 v0, v23, v25
	v_min_u32_e32 v22, v23, v25
	v_max_u32_e32 v23, v24, v15
	v_min_u32_e32 v15, v24, v15
	v_max_u32_e32 v24, v14, v13
	v_min_u32_e32 v13, v14, v13
	v_max_u32_e32 v14, v12, v1
	v_min_u32_e32 v1, v12, v1
	v_max_u32_e32 v25, v0, v23
	v_min_u32_e32 v0, v0, v23
	v_max_u32_e32 v12, v22, v15
	v_min_u32_e32 v15, v22, v15
	v_max_u32_e32 v22, v24, v14
	v_min_u32_e32 v14, v24, v14
	v_max_u32_e32 v23, v13, v1
	v_min_u32_e32 v1, v13, v1
	v_max_u32_e32 v13, v12, v0
	v_min_u32_e32 v0, v12, v0
	v_max_u32_e32 v24, v23, v14
	v_min_u32_e32 v14, v23, v14
	v_max_u32_e32 v72, v25, v22
	v_min_u32_e32 v22, v25, v22
	v_max_u32_e32 v23, v13, v24
	v_min_u32_e32 v24, v13, v24
	v_max_u32_e32 v25, v0, v14
	v_min_u32_e32 v0, v0, v14
	v_max_u32_e32 v14, v15, v1
	v_max_u32_e32 v85, v11, v26
	v_min_u32_e32 v86, v11, v26
	v_min_u32_e32 v79, v15, v1
	v_max_u32_e32 v1, v25, v22
	v_min_u32_e32 v25, v25, v22
	v_max_u32_e32 v26, v14, v24
	v_min_u32_e32 v27, v14, v24
	v_max_u32_e32 v73, v23, v1
	v_min_u32_e32 v74, v23, v1
	v_max_u32_e32 v75, v26, v25
	v_min_u32_e32 v76, v26, v25
	v_max_u32_e32 v77, v27, v0
	v_min_u32_e32 v78, v27, v0
	v_max_u32_e32 v0, v44, v28
	v_min_u32_e32 v1, v44, v28
	v_max_u32_e32 v26, v32, v36
	v_min_u32_e32 v27, v32, v36
	v_max_u32_e32 v28, v40, v33
	v_min_u32_e32 v30, v40, v33
	v_max_u32_e32 v29, v0, v26
	v_min_u32_e32 v0, v0, v26
	v_max_u32_e32 v26, v1, v27
	v_min_u32_e32 v1, v1, v27
	v_max_u32_e32 v27, v28, v31
	v_min_u32_e32 v28, v28, v31
	v_max_u32_e32 v31, v30, v2
	v_min_u32_e32 v2, v30, v2
	v_max_u32_e32 v30, v26, v0
	v_min_u32_e32 v0, v26, v0
	v_max_u32_e32 v32, v31, v28
	v_min_u32_e32 v28, v31, v28
	v_max_u32_e32 v88, v29, v27
	v_min_u32_e32 v29, v29, v27
	v_max_u32_e32 v31, v30, v32
	v_min_u32_e32 v30, v30, v32
	v_max_u32_e32 v32, v0, v28
	v_min_u32_e32 v0, v0, v28
	v_max_u32_e32 v28, v1, v2
	v_min_u32_e32 v95, v1, v2
	v_max_u32_e32 v1, v32, v29
	v_min_u32_e32 v2, v32, v29
	v_max_u32_e32 v32, v28, v30
	v_min_u32_e32 v33, v28, v30
	v_max_u32_e32 v89, v31, v1
	v_min_u32_e32 v90, v31, v1
	v_max_u32_e32 v91, v32, v2
	v_min_u32_e32 v92, v32, v2
	v_max_u32_e32 v93, v33, v0
	v_min_u32_e32 v94, v33, v0
	v_max_u32_e32 v0, v52, v51
	v_min_u32_e32 v1, v52, v51
	v_max_u32_e32 v2, v50, v37
	v_min_u32_e32 v34, v50, v37
	v_min_u32_e32 v36, v41, v45
	v_max_u32_e32 v37, v49, v3
	v_min_u32_e32 v3, v49, v3
	v_max_u32_e32 v38, v0, v2
	v_min_u32_e32 v0, v0, v2
	v_max_u32_e32 v2, v1, v34
	v_min_u32_e32 v1, v1, v34
	v_max_u32_e32 v39, v35, v37
	v_min_u32_e32 v34, v35, v37
	v_max_u32_e32 v35, v36, v3
	v_min_u32_e32 v3, v36, v3
	v_max_u32_e32 v36, v2, v0
	v_min_u32_e32 v0, v2, v0
	v_max_u32_e32 v2, v35, v34
	v_min_u32_e32 v35, v35, v34
	v_max_u32_e32 v96, v38, v39
	v_min_u32_e32 v37, v38, v39
	v_max_u32_e32 v38, v36, v2
	v_min_u32_e32 v2, v36, v2
	v_max_u32_e32 v36, v0, v35
	v_max_u32_e32 v39, v1, v3
	v_min_u32_e32 v0, v0, v35
	v_min_u32_e32 v103, v1, v3
	v_max_u32_e32 v1, v36, v37
	v_min_u32_e32 v3, v36, v37
	v_max_u32_e32 v40, v39, v2
	v_min_u32_e32 v2, v39, v2
	v_max_u32_e32 v97, v38, v1
	v_min_u32_e32 v98, v38, v1
	v_max_u32_e32 v99, v40, v3
	v_min_u32_e32 v100, v40, v3
	v_max_u32_e32 v101, v2, v0
	v_min_u32_e32 v102, v2, v0
	v_mov_b32_e32 v0, 0
	v_mov_b32_e32 v1, 0
	v_mov_b32_e32 v2, 0
	v_mov_b32_e32 v3, 0

.LBB0_1374:
	s_or_b64 exec, exec, s[0:1]
	v_add_f32_e32 v25, v25, v29
	v_cmp_lt_i32_e32 vcc, -1, v25
	v_add_f32_e32 v22, v22, v23
	v_add_f32_e32 v10, v10, v11
	v_cndmask_b32_e32 v29, -1, v217, vcc
	v_cmp_lt_i32_e32 vcc, -1, v22
	v_add_f32_e32 v4, v4, v5
	v_bitop3_b32 v25, v29, s59, v25 bitop3:0x48
	v_cndmask_b32_e32 v23, -1, v217, vcc
	v_cmp_lt_i32_e32 vcc, -1, v10
	v_bitop3_b32 v22, v23, s59, v22 bitop3:0x48
	v_bitop3_b32 v29, v25, s54, v174 bitop3:0x36
	v_cndmask_b32_e32 v11, -1, v217, vcc
	v_cmp_lt_i32_e32 vcc, -1, v4
	v_bitop3_b32 v10, v11, s59, v10 bitop3:0x48
	v_bitop3_b32 v23, v10, s54, v174 bitop3:0x36
	v_cndmask_b32_e32 v5, -1, v217, vcc
	v_bitop3_b32 v4, v5, s59, v4 bitop3:0x48
	v_bitop3_b32 v4, v4, s54, v174 bitop3:0x36
	v_max_u32_e32 v5, v4, v7
	v_min_u32_e32 v4, v4, v7
	v_max_u32_e32 v7, v6, v9
	v_min_u32_e32 v6, v6, v9
	v_max_u32_e32 v76, v5, v7
	v_min_u32_e32 v5, v5, v7
	v_max_u32_e32 v7, v4, v6
	v_bitop3_b32 v25, v22, s54, v174 bitop3:0x36
	v_min_u32_e32 v79, v4, v6
	v_max_u32_e32 v77, v7, v5
	v_min_u32_e32 v78, v7, v5
	v_max_u32_e32 v4, v23, v8
	v_min_u32_e32 v5, v23, v8
	v_max_u32_e32 v6, v13, v12
	v_min_u32_e32 v7, v13, v12
	v_max_u32_e32 v72, v4, v6
	v_min_u32_e32 v4, v4, v6
	v_max_u32_e32 v6, v5, v7
	v_min_u32_e32 v75, v5, v7
	v_max_u32_e32 v73, v6, v4
	v_min_u32_e32 v74, v6, v4
	v_max_u32_e32 v4, v25, v15
	v_min_u32_e32 v5, v25, v15
	v_max_u32_e32 v6, v14, v24
	v_min_u32_e32 v7, v14, v24
	v_max_u32_e32 v80, v4, v6
	v_min_u32_e32 v4, v4, v6
	v_max_u32_e32 v6, v5, v7
	v_min_u32_e32 v83, v5, v7
	v_max_u32_e32 v81, v6, v4
	v_min_u32_e32 v82, v6, v4
	v_max_u32_e32 v4, v29, v26
	v_min_u32_e32 v5, v29, v26
	v_max_u32_e32 v6, v28, v27
	v_min_u32_e32 v7, v28, v27
	v_max_u32_e32 v84, v4, v6
	v_min_u32_e32 v4, v4, v6
	v_max_u32_e32 v6, v5, v7
	v_min_u32_e32 v87, v5, v7
	v_max_u32_e32 v85, v6, v4
	v_min_u32_e32 v86, v6, v4
	s_mov_b32 s40, 0
	v_mov_b32_e32 v7, 0
	v_mov_b32_e32 v6, 0
	v_mov_b32_e32 v5, 0
	v_mov_b32_e32 v4, 0
	s_waitcnt lgkmcnt(0)
